# sample-row up-projection items rewritten: operand loads streamed through three buffers with counted waits; memory item rebalance
# baseline (speedup 1.0000x reference)
; DI void p2_mixers(const Params& p, LAS unsigned char* lds) {
;     ...
;         int m0 = -1, m1 = -1;
;         if (NGW == 2048) { if (gw >= 256) m0 = gw - 256; if (gw >= 1536 && gw < 1792) m1 = gw + 256; if (gw >= 256 && gw < 384) m1 = 2048 + gw - 256; }
;         for (int k = 0;; ++k) {
;             int it;
;             if (NGW == 2048) { if (k >= 2) break; it = k ? m1 : m0; if (it < 0) continue; }
;             else { it = gw + k * NGW; if (it >= 2176) break; }
;             AttnItem a;
;             a.qld = 256; a.kld = 256; a.zold = 256; a.vtld = 256; a.nkeys = 256; a.nkb = 8; a.bias = nullptr; a.qpos0 = 0;
;             if (it < 2048) {
;                 const int head = it & 3, tg = it >> 2, tq = 32 * tg, b = tq >> 13;
;                 a.q = (const bf16_t*)(ws + OFF_QM) + (size_t)tq * 256 + head * 64; a.nq = 32;
;                 a.k = (const bf16_t*)(ws + OFF_MK) + (size_t)b * 65536 + head * 64;
;                 a.vt = (const bf16_t*)(ws + OFF_MVT) + (size_t)(b * 256 + head * 64) * 256;
;                 a.zo = (bf16_t*)(ws + OFF_ZM) + (size_t)tq * 256 + head * 64;
.LBB0_982:
	s_and_b64 vcc, exec, s[12:13]
	s_cbranch_vccz .LBB0_987
	s_mov_b32 s101, -1
	s_lshr_b32 s12, s48, 8
	s_and_b32 s13, s48, 0xff
	s_cmpk_ge_u32 s13, 0x80
	s_cbranch_scc0 .Lat_mem_go
	s_add_i32 s14, s48, 0xffffff00
	s_cmp_eq_u32 s39, s14
	s_cbranch_scc0 .Lat_mem_go
	s_cmp_eq_u32 s12, 5
	s_cbranch_scc1 .Lat_ret_mem
	s_cmp_eq_u32 s12, 7
	s_cbranch_scc0 .Lat_mem_go
	s_add_i32 s101, s13, 0x400
.Lat_mem_go:
	s_cmpk_gt_i32 s39, 0x7ff
	s_cbranch_scc1 .Lat_mem_s2_1001
	s_and_b32 s12, s39, 3
	s_lshr_b32 s13, s39, 2
	s_lshl_b32 s19, s13, 5
	s_lshr_b32 s15, s19, 13
	s_lshl_b32 s21, s12, 7
	s_lshl_b32 s32, s15, 17
	s_add_i32 s32, s32, s21
	s_add_u32 s52, s44, 0xead0000
	s_addc_u32 s53, s45, 0
	s_add_u32 s52, s52, s32
	s_addc_u32 s53, s53, 0
	s_lshl_b32 s32, s15, 8
	s_lshl_b32 s14, s12, 6
	s_add_i32 s32, s32, s14
	s_lshl_b32 s32, s32, 9
	s_add_u32 s54, s44, 0xeb10000
	s_addc_u32 s55, s45, 0
	s_add_u32 s54, s54, s32
	s_addc_u32 s55, s55, 0
	s_mov_b32 s63, 32
	s_branch .Lat_mem_done_1002

; DI void p2_mixers(const Params& p, LAS unsigned char* lds) {
;     ...
;         for (int k = 0;; ++k) {
;             int it;
;             if (NGW == 2048) { if (k >= 2) break; it = k ? m1 : m0; if (it < 0) continue; }
;             else { it = gw + k * NGW; if (it >= 2176) break; }
.Lat_ret_mem:
	s_cmp_lt_i32 s101, 0
	s_cbranch_scc1 .Lat_mem_fin
	s_mov_b32 s39, s101
	s_mov_b32 s101, -1
	s_branch .Lat_mem_go

; DI void sample_up_item(const Params& p, int item, int lane) {
;     unsigned char* ws = p.ws;
;     const int qi = lane & 31, hh = lane >> 5, tg = item >> 5, nb = item & 31;
;     const int tok = T_P + 32 * tg + qi, wrow = wt_row(nb) + qi;
;     f32x16 tot;
; #pragma unroll
;     for (int r = 0; r < 16; ++r) tot[r] = 0.f;
; #pragma unroll
;     for (int br = 0; br < 3; ++br) {
;         const int ld = br == 2 ? 256 : 512;
;         const bf16_t* gp = (const bf16_t*)(ws + (br == 0 ? OFF_ZA : (br == 1 ? OFF_ZB : OFF_ZM))) + (size_t)tok * ld + 8 * hh;
;         const bf16_t* wp = (const bf16_t*)(ws + (br == 0 ? OFF_WUPA : (br == 1 ? OFF_WUPB : OFF_WUPM))) + (size_t)wrow * ld + 8 * hh;
;         f32x16 acc;
; #pragma unroll
;         for (int r = 0; r < 16; ++r) acc[r] = 0.f;
; #pragma unroll 1
;         for (int c0 = 0; c0 < ld / 16; c0 += 16) {
;             bf16x8 wa[16], ga[16];
; #pragma unroll
;             for (int j = 0; j < 16; ++j) { wa[j] = *(const bf16x8*)(wp + 16 * (c0 + j)); ga[j] = *(const bf16x8*)(gp + 16 * (c0 + j)); }
.Lsup_item:
	s_add_u32 s16, s44, 0x87d0000
	s_addc_u32 s17, s45, 0
	s_add_u32 s18, s44, 0xe80000
	s_addc_u32 s19, s45, 0
	s_add_u32 s20, s44, 0xc9d0000
	s_addc_u32 s21, s45, 0
	s_add_u32 s22, s44, 0xf80000
	s_addc_u32 s23, s45, 0
	s_add_u32 s24, s44, 0xe290000
	s_addc_u32 s25, s45, 0
	s_add_u32 s26, s44, 0x1080000
	s_addc_u32 s27, s45, 0
	s_add_u32 s28, s44, 0xf390000
	s_addc_u32 s29, s45, 0
	s_add_u32 s30, s44, 0x5700000
	s_addc_u32 s31, s45, 0
	v_and_b32_e32 v224, 31, v203
	v_bfe_u32 v225, v203, 5, 1
	s_lshr_b32 s4, s12, 5
	s_lshl_b32 s4, s4, 5
	s_add_i32 s4, s4, 0x4000
	s_and_b32 s5, s12, 31
	s_lshr_b32 s6, s5, 3
	s_lshl_b32 s6, s6, 8
	s_and_b32 s7, s5, 1
	s_lshl_b32 s7, s7, 7
	s_add_i32 s6, s6, s7
	s_bfe_u32 s7, s5, 0x20001
	s_lshl_b32 s7, s7, 5
	s_add_i32 s6, s6, s7
	v_add_u32_e32 v186, s4, v224
	v_lshlrev_b32_e32 v183, 10, v186
	v_lshl_add_u32 v183, v225, 4, v183
	v_add_u32_e32 v254, s6, v224
	v_lshlrev_b32_e32 v182, 10, v254
	v_lshl_add_u32 v182, v225, 4, v182
	v_subrev_u32_e32 v184, 0x4000, v186
	v_mul_u32_u24_e32 v184, 0x1800, v184
	s_lshl_b32 s7, s5, 6
	v_lshl_add_u32 v184, v225, 3, v184
	v_add_u32_e32 v184, s7, v184
	v_lshlrev_b32_e32 v185, 11, v186
	v_lshl_add_u32 v185, v225, 3, v185
	v_add_u32_e32 v185, s7, v185
	v_mov_b32_e32 v190, 0
	v_mov_b32_e32 v191, 0
	v_mov_b32_e32 v192, 0
	v_mov_b32_e32 v193, 0
	v_mov_b32_e32 v194, 0
	v_mov_b32_e32 v195, 0
	v_mov_b32_e32 v196, 0
	v_mov_b32_e32 v197, 0
	v_mov_b32_e32 v198, 0
	v_mov_b32_e32 v199, 0
	v_mov_b32_e32 v200, 0
	v_mov_b32_e32 v201, 0
	v_mov_b32_e32 v202, 0
	v_mov_b32_e32 v108, 0
	v_mov_b32_e32 v109, 0
	v_mov_b32_e32 v110, 0
	s_add_u32 s6, s28, 0x0
	s_addc_u32 s7, s29, 0
	global_load_dwordx2 v[240:241], v184, s[6:7]
	global_load_dwordx2 v[242:243], v184, s[6:7] offset:16
	global_load_dwordx2 v[244:245], v184, s[6:7] offset:32
	global_load_dwordx2 v[246:247], v184, s[6:7] offset:48
	global_load_dwordx4 v[0:3], v182, s[18:19]
	global_load_dwordx4 v[4:7], v183, s[16:17]
	global_load_dwordx4 v[8:11], v182, s[18:19] offset:32
	global_load_dwordx4 v[12:15], v183, s[16:17] offset:32
	global_load_dwordx4 v[16:19], v182, s[18:19] offset:64
	global_load_dwordx4 v[20:23], v183, s[16:17] offset:64
	global_load_dwordx4 v[24:27], v182, s[18:19] offset:96
	global_load_dwordx4 v[28:31], v183, s[16:17] offset:96
	global_load_dwordx4 v[32:35], v182, s[18:19] offset:128
	global_load_dwordx4 v[36:39], v183, s[16:17] offset:128
	global_load_dwordx4 v[40:43], v182, s[18:19] offset:160
	global_load_dwordx4 v[44:47], v183, s[16:17] offset:160
	global_load_dwordx4 v[48:51], v182, s[18:19] offset:192
	global_load_dwordx4 v[52:55], v183, s[16:17] offset:192
	global_load_dwordx4 v[56:59], v182, s[18:19] offset:224
	global_load_dwordx4 v[60:63], v183, s[16:17] offset:224
	global_load_dwordx4 v[116:119], v182, s[18:19] offset:256
	global_load_dwordx4 v[120:123], v183, s[16:17] offset:256
	global_load_dwordx4 v[124:127], v182, s[18:19] offset:288
	global_load_dwordx4 v[128:131], v183, s[16:17] offset:288
	global_load_dwordx4 v[132:135], v182, s[18:19] offset:320
	global_load_dwordx4 v[136:139], v183, s[16:17] offset:320
	global_load_dwordx4 v[140:143], v182, s[18:19] offset:352
	global_load_dwordx4 v[144:147], v183, s[16:17] offset:352
	global_load_dwordx4 v[148:151], v182, s[18:19] offset:384
	global_load_dwordx4 v[152:155], v183, s[16:17] offset:384
	global_load_dwordx4 v[156:159], v182, s[18:19] offset:416
	global_load_dwordx4 v[160:163], v183, s[16:17] offset:416
	global_load_dwordx4 v[164:167], v182, s[18:19] offset:448
	global_load_dwordx4 v[168:171], v183, s[16:17] offset:448
	global_load_dwordx4 v[172:175], v182, s[18:19] offset:480
	global_load_dwordx4 v[176:179], v183, s[16:17] offset:480
	global_load_dwordx4 v[64:67], v182, s[18:19] offset:512
	global_load_dwordx4 v[68:71], v183, s[16:17] offset:512
	global_load_dwordx4 v[72:75], v182, s[18:19] offset:544
	global_load_dwordx4 v[76:79], v183, s[16:17] offset:544
	global_load_dwordx4 v[80:83], v182, s[18:19] offset:576
	global_load_dwordx4 v[84:87], v183, s[16:17] offset:576
	global_load_dwordx4 v[88:91], v182, s[18:19] offset:608
	global_load_dwordx4 v[92:95], v183, s[16:17] offset:608
	global_load_dwordx4 v[96:99], v182, s[18:19] offset:640
	global_load_dwordx4 v[100:103], v183, s[16:17] offset:640
	global_load_dwordx4 v[104:107], v182, s[18:19] offset:672
	global_load_dwordx4 v[204:207], v183, s[16:17] offset:672
	global_load_dwordx4 v[208:211], v182, s[18:19] offset:704
	global_load_dwordx4 v[212:215], v183, s[16:17] offset:704
	global_load_dwordx4 v[216:219], v182, s[18:19] offset:736
	global_load_dwordx4 v[220:223], v183, s[16:17] offset:736
	s_waitcnt vmcnt(32)
	v_mfma_f32_32x32x16_bf16 v[224:239], v[0:3], v[4:7], 0
	v_mfma_f32_32x32x16_bf16 v[224:239], v[8:11], v[12:15], v[224:239]
	v_mfma_f32_32x32x16_bf16 v[224:239], v[16:19], v[20:23], v[224:239]
	v_mfma_f32_32x32x16_bf16 v[224:239], v[24:27], v[28:31], v[224:239]
	v_mfma_f32_32x32x16_bf16 v[224:239], v[32:35], v[36:39], v[224:239]
	v_mfma_f32_32x32x16_bf16 v[224:239], v[40:43], v[44:47], v[224:239]
	v_mfma_f32_32x32x16_bf16 v[224:239], v[48:51], v[52:55], v[224:239]
	v_mfma_f32_32x32x16_bf16 v[224:239], v[56:59], v[60:63], v[224:239]
	global_load_dwordx4 v[0:3], v182, s[18:19] offset:768
	global_load_dwordx4 v[4:7], v183, s[16:17] offset:768
	global_load_dwordx4 v[8:11], v182, s[18:19] offset:800
	global_load_dwordx4 v[12:15], v183, s[16:17] offset:800
	global_load_dwordx4 v[16:19], v182, s[18:19] offset:832
	global_load_dwordx4 v[20:23], v183, s[16:17] offset:832
	global_load_dwordx4 v[24:27], v182, s[18:19] offset:864
	global_load_dwordx4 v[28:31], v183, s[16:17] offset:864
	global_load_dwordx4 v[32:35], v182, s[18:19] offset:896
	global_load_dwordx4 v[36:39], v183, s[16:17] offset:896
	global_load_dwordx4 v[40:43], v182, s[18:19] offset:928
	global_load_dwordx4 v[44:47], v183, s[16:17] offset:928
	global_load_dwordx4 v[48:51], v182, s[18:19] offset:960
	global_load_dwordx4 v[52:55], v183, s[16:17] offset:960
	global_load_dwordx4 v[56:59], v182, s[18:19] offset:992
	global_load_dwordx4 v[60:63], v183, s[16:17] offset:992
	s_waitcnt vmcnt(32)
; DI float bflo(unsigned w) { return __uint_as_float(w << 16); }
; DI float bfhi(unsigned w) { return __uint_as_float(w & 0xffff0000u); }
; #define MFMA32(a, b, c) __builtin_amdgcn_mfma_f32_32x32x16_bf16((a), (b), (c), 0, 0, 0)
; DI void sample_up_item(const Params& p, int item, int lane) {
;     ...
;     for (int br = 0; br < 3; ++br) {
;         const int ld = br == 2 ? 256 : 512;
;         const bf16_t* gp = (const bf16_t*)(ws + (br == 0 ? OFF_ZA : (br == 1 ? OFF_ZB : OFF_ZM))) + (size_t)tok * ld + 8 * hh;
;         const bf16_t* wp = (const bf16_t*)(ws + (br == 0 ? OFF_WUPA : (br == 1 ? OFF_WUPB : OFF_WUPM))) + (size_t)wrow * ld + 8 * hh;
;         f32x16 acc;
; #pragma unroll
;         for (int r = 0; r < 16; ++r) acc[r] = 0.f;
; #pragma unroll 1
;         for (int c0 = 0; c0 < ld / 16; c0 += 16) {
;             bf16x8 wa[16], ga[16];
; #pragma unroll
;             for (int j = 0; j < 16; ++j) { wa[j] = *(const bf16x8*)(wp + 16 * (c0 + j)); ga[j] = *(const bf16x8*)(gp + 16 * (c0 + j)); }
;             __builtin_amdgcn_sched_barrier(0);
; #pragma unroll
;             for (int j = 0; j < 16; ++j) acc = MFMA32(wa[j], ga[j], acc);
;             __builtin_amdgcn_sched_barrier(0);
;         }
;         const bf16_t* sg = (const bf16_t*)(ws + OFF_SGS) + (size_t)(tok - T_P) * 3072 + br * 1024 + 32 * nb + 4 * hh;
; #pragma unroll
;         for (int g = 0; g < 4; ++g) {
;             const u32x2 z = *(const u32x2*)(sg + 8 * g);
;             tot[4 * g] += acc[4 * g] * bflo(z.x); tot[4 * g + 1] += acc[4 * g + 1] * bfhi(z.x); tot[4 * g + 2] += acc[4 * g + 2] * bflo(z.y); tot[4 * g + 3] += acc[4 * g + 3] * bfhi(z.y);
	v_mfma_f32_32x32x16_bf16 v[224:239], v[116:119], v[120:123], v[224:239]
	v_mfma_f32_32x32x16_bf16 v[224:239], v[124:127], v[128:131], v[224:239]
	v_mfma_f32_32x32x16_bf16 v[224:239], v[132:135], v[136:139], v[224:239]
	v_mfma_f32_32x32x16_bf16 v[224:239], v[140:143], v[144:147], v[224:239]
	v_mfma_f32_32x32x16_bf16 v[224:239], v[148:151], v[152:155], v[224:239]
	v_mfma_f32_32x32x16_bf16 v[224:239], v[156:159], v[160:163], v[224:239]
	v_mfma_f32_32x32x16_bf16 v[224:239], v[164:167], v[168:171], v[224:239]
	v_mfma_f32_32x32x16_bf16 v[224:239], v[172:175], v[176:179], v[224:239]
	s_add_u32 s6, s28, 0x800
	s_addc_u32 s7, s29, 0
	global_load_dwordx2 v[248:249], v184, s[6:7]
	global_load_dwordx2 v[250:251], v184, s[6:7] offset:16
	global_load_dwordx2 v[252:253], v184, s[6:7] offset:32
	global_load_dwordx2 v[180:181], v184, s[6:7] offset:48
	global_load_dwordx4 v[116:119], v182, s[22:23]
	global_load_dwordx4 v[120:123], v183, s[20:21]
	global_load_dwordx4 v[124:127], v182, s[22:23] offset:32
	global_load_dwordx4 v[128:131], v183, s[20:21] offset:32
	global_load_dwordx4 v[132:135], v182, s[22:23] offset:64
	global_load_dwordx4 v[136:139], v183, s[20:21] offset:64
	global_load_dwordx4 v[140:143], v182, s[22:23] offset:96
	global_load_dwordx4 v[144:147], v183, s[20:21] offset:96
	global_load_dwordx4 v[148:151], v182, s[22:23] offset:128
	global_load_dwordx4 v[152:155], v183, s[20:21] offset:128
	global_load_dwordx4 v[156:159], v182, s[22:23] offset:160
	global_load_dwordx4 v[160:163], v183, s[20:21] offset:160
	global_load_dwordx4 v[164:167], v182, s[22:23] offset:192
	global_load_dwordx4 v[168:171], v183, s[20:21] offset:192
	global_load_dwordx4 v[172:175], v182, s[22:23] offset:224
	global_load_dwordx4 v[176:179], v183, s[20:21] offset:224
	s_waitcnt vmcnt(36)
	v_mfma_f32_32x32x16_bf16 v[224:239], v[64:67], v[68:71], v[224:239]
	v_mfma_f32_32x32x16_bf16 v[224:239], v[72:75], v[76:79], v[224:239]
	v_mfma_f32_32x32x16_bf16 v[224:239], v[80:83], v[84:87], v[224:239]
	v_mfma_f32_32x32x16_bf16 v[224:239], v[88:91], v[92:95], v[224:239]
	v_mfma_f32_32x32x16_bf16 v[224:239], v[96:99], v[100:103], v[224:239]
	v_mfma_f32_32x32x16_bf16 v[224:239], v[104:107], v[204:207], v[224:239]
	v_mfma_f32_32x32x16_bf16 v[224:239], v[208:211], v[212:215], v[224:239]
	v_mfma_f32_32x32x16_bf16 v[224:239], v[216:219], v[220:223], v[224:239]
	global_load_dwordx4 v[64:67], v182, s[22:23] offset:256
	global_load_dwordx4 v[68:71], v183, s[20:21] offset:256
	global_load_dwordx4 v[72:75], v182, s[22:23] offset:288
	global_load_dwordx4 v[76:79], v183, s[20:21] offset:288
	global_load_dwordx4 v[80:83], v182, s[22:23] offset:320
	global_load_dwordx4 v[84:87], v183, s[20:21] offset:320
	global_load_dwordx4 v[88:91], v182, s[22:23] offset:352
	global_load_dwordx4 v[92:95], v183, s[20:21] offset:352
	global_load_dwordx4 v[96:99], v182, s[22:23] offset:384
	global_load_dwordx4 v[100:103], v183, s[20:21] offset:384
	global_load_dwordx4 v[104:107], v182, s[22:23] offset:416
	global_load_dwordx4 v[204:207], v183, s[20:21] offset:416
	global_load_dwordx4 v[208:211], v182, s[22:23] offset:448
	global_load_dwordx4 v[212:215], v183, s[20:21] offset:448
	global_load_dwordx4 v[216:219], v182, s[22:23] offset:480
	global_load_dwordx4 v[220:223], v183, s[20:21] offset:480
	s_waitcnt vmcnt(36)
	v_mfma_f32_32x32x16_bf16 v[224:239], v[0:3], v[4:7], v[224:239]
	v_mfma_f32_32x32x16_bf16 v[224:239], v[8:11], v[12:15], v[224:239]
	v_mfma_f32_32x32x16_bf16 v[224:239], v[16:19], v[20:23], v[224:239]
	v_mfma_f32_32x32x16_bf16 v[224:239], v[24:27], v[28:31], v[224:239]
	v_mfma_f32_32x32x16_bf16 v[224:239], v[32:35], v[36:39], v[224:239]
	v_mfma_f32_32x32x16_bf16 v[224:239], v[40:43], v[44:47], v[224:239]
	v_mfma_f32_32x32x16_bf16 v[224:239], v[48:51], v[52:55], v[224:239]
	v_mfma_f32_32x32x16_bf16 v[224:239], v[56:59], v[60:63], v[224:239]
	global_load_dwordx4 v[0:3], v182, s[22:23] offset:512
	global_load_dwordx4 v[4:7], v183, s[20:21] offset:512
	global_load_dwordx4 v[8:11], v182, s[22:23] offset:544
	global_load_dwordx4 v[12:15], v183, s[20:21] offset:544
	global_load_dwordx4 v[16:19], v182, s[22:23] offset:576
	global_load_dwordx4 v[20:23], v183, s[20:21] offset:576
	global_load_dwordx4 v[24:27], v182, s[22:23] offset:608
	global_load_dwordx4 v[28:31], v183, s[20:21] offset:608
	global_load_dwordx4 v[32:35], v182, s[22:23] offset:640
	global_load_dwordx4 v[36:39], v183, s[20:21] offset:640
	global_load_dwordx4 v[40:43], v182, s[22:23] offset:672
	global_load_dwordx4 v[44:47], v183, s[20:21] offset:672
	global_load_dwordx4 v[48:51], v182, s[22:23] offset:704
	global_load_dwordx4 v[52:55], v183, s[20:21] offset:704
	global_load_dwordx4 v[56:59], v182, s[22:23] offset:736
	global_load_dwordx4 v[60:63], v183, s[20:21] offset:736
	s_nop 7
	s_nop 3
	v_lshlrev_b32_e32 v186, 16, v240
	v_fma_f32 v190, v224, v186, v190
	v_and_b32_e32 v186, 0xffff0000, v240
	v_fma_f32 v191, v225, v186, v191
	v_lshlrev_b32_e32 v186, 16, v241
	v_fma_f32 v192, v226, v186, v192
	v_and_b32_e32 v186, 0xffff0000, v241
	v_fma_f32 v193, v227, v186, v193
	v_lshlrev_b32_e32 v186, 16, v242
	v_fma_f32 v194, v228, v186, v194
	v_and_b32_e32 v186, 0xffff0000, v242
	v_fma_f32 v195, v229, v186, v195
	v_lshlrev_b32_e32 v186, 16, v243
	v_fma_f32 v196, v230, v186, v196
	v_and_b32_e32 v186, 0xffff0000, v243
	v_fma_f32 v197, v231, v186, v197
	v_lshlrev_b32_e32 v186, 16, v244
	v_fma_f32 v198, v232, v186, v198
	v_and_b32_e32 v186, 0xffff0000, v244
	v_fma_f32 v199, v233, v186, v199
	v_lshlrev_b32_e32 v186, 16, v245
	v_fma_f32 v200, v234, v186, v200
	v_and_b32_e32 v186, 0xffff0000, v245
	v_fma_f32 v201, v235, v186, v201
	v_lshlrev_b32_e32 v186, 16, v246
	v_fma_f32 v202, v236, v186, v202
	v_and_b32_e32 v186, 0xffff0000, v246
	v_fma_f32 v108, v237, v186, v108
	v_lshlrev_b32_e32 v186, 16, v247
	v_fma_f32 v109, v238, v186, v109
	v_and_b32_e32 v186, 0xffff0000, v247
	v_fma_f32 v110, v239, v186, v110
	s_waitcnt vmcnt(32)
; #define MFMA32(a, b, c) __builtin_amdgcn_mfma_f32_32x32x16_bf16((a), (b), (c), 0, 0, 0)
; DI void sample_up_item(const Params& p, int item, int lane) {
;     ...
;     for (int br = 0; br < 3; ++br) {
;         const int ld = br == 2 ? 256 : 512;
;         const bf16_t* gp = (const bf16_t*)(ws + (br == 0 ? OFF_ZA : (br == 1 ? OFF_ZB : OFF_ZM))) + (size_t)tok * ld + 8 * hh;
;         const bf16_t* wp = (const bf16_t*)(ws + (br == 0 ? OFF_WUPA : (br == 1 ? OFF_WUPB : OFF_WUPM))) + (size_t)wrow * ld + 8 * hh;
;         f32x16 acc;
; #pragma unroll
;         for (int r = 0; r < 16; ++r) acc[r] = 0.f;
; #pragma unroll 1
;         for (int c0 = 0; c0 < ld / 16; c0 += 16) {
;             bf16x8 wa[16], ga[16];
; #pragma unroll
;             for (int j = 0; j < 16; ++j) { wa[j] = *(const bf16x8*)(wp + 16 * (c0 + j)); ga[j] = *(const bf16x8*)(gp + 16 * (c0 + j)); }
;             __builtin_amdgcn_sched_barrier(0);
; #pragma unroll
;             for (int j = 0; j < 16; ++j) acc = MFMA32(wa[j], ga[j], acc);
;             __builtin_amdgcn_sched_barrier(0);
;         }
;         const bf16_t* sg = (const bf16_t*)(ws + OFF_SGS) + (size_t)(tok - T_P) * 3072 + br * 1024 + 32 * nb + 4 * hh;
	v_mfma_f32_32x32x16_bf16 v[224:239], v[116:119], v[120:123], 0
	v_mfma_f32_32x32x16_bf16 v[224:239], v[124:127], v[128:131], v[224:239]
	v_mfma_f32_32x32x16_bf16 v[224:239], v[132:135], v[136:139], v[224:239]
	v_mfma_f32_32x32x16_bf16 v[224:239], v[140:143], v[144:147], v[224:239]
	v_mfma_f32_32x32x16_bf16 v[224:239], v[148:151], v[152:155], v[224:239]
	v_mfma_f32_32x32x16_bf16 v[224:239], v[156:159], v[160:163], v[224:239]
	v_mfma_f32_32x32x16_bf16 v[224:239], v[164:167], v[168:171], v[224:239]
	v_mfma_f32_32x32x16_bf16 v[224:239], v[172:175], v[176:179], v[224:239]
	global_load_dwordx4 v[116:119], v182, s[22:23] offset:768
	global_load_dwordx4 v[120:123], v183, s[20:21] offset:768
	global_load_dwordx4 v[124:127], v182, s[22:23] offset:800
	global_load_dwordx4 v[128:131], v183, s[20:21] offset:800
	global_load_dwordx4 v[132:135], v182, s[22:23] offset:832
	global_load_dwordx4 v[136:139], v183, s[20:21] offset:832
	global_load_dwordx4 v[140:143], v182, s[22:23] offset:864
	global_load_dwordx4 v[144:147], v183, s[20:21] offset:864
	global_load_dwordx4 v[148:151], v182, s[22:23] offset:896
	global_load_dwordx4 v[152:155], v183, s[20:21] offset:896
	global_load_dwordx4 v[156:159], v182, s[22:23] offset:928
	global_load_dwordx4 v[160:163], v183, s[20:21] offset:928
	global_load_dwordx4 v[164:167], v182, s[22:23] offset:960
	global_load_dwordx4 v[168:171], v183, s[20:21] offset:960
	global_load_dwordx4 v[172:175], v182, s[22:23] offset:992
	global_load_dwordx4 v[176:179], v183, s[20:21] offset:992
	s_waitcnt vmcnt(32)
	v_mfma_f32_32x32x16_bf16 v[224:239], v[64:67], v[68:71], v[224:239]
	v_mfma_f32_32x32x16_bf16 v[224:239], v[72:75], v[76:79], v[224:239]
	v_mfma_f32_32x32x16_bf16 v[224:239], v[80:83], v[84:87], v[224:239]
	v_mfma_f32_32x32x16_bf16 v[224:239], v[88:91], v[92:95], v[224:239]
	v_mfma_f32_32x32x16_bf16 v[224:239], v[96:99], v[100:103], v[224:239]
	v_mfma_f32_32x32x16_bf16 v[224:239], v[104:107], v[204:207], v[224:239]
	v_mfma_f32_32x32x16_bf16 v[224:239], v[208:211], v[212:215], v[224:239]
	v_mfma_f32_32x32x16_bf16 v[224:239], v[216:219], v[220:223], v[224:239]
	s_add_u32 s6, s28, 0x1000
	s_addc_u32 s7, s29, 0
	global_load_dwordx2 v[240:241], v184, s[6:7]
	global_load_dwordx2 v[242:243], v184, s[6:7] offset:16
	global_load_dwordx2 v[244:245], v184, s[6:7] offset:32
	global_load_dwordx2 v[246:247], v184, s[6:7] offset:48
	v_bfe_u32 v186, v203, 5, 1
	v_lshl_add_u32 v186, v186, 4, v182
	v_lshrrev_b32_e32 v186, 1, v186
	v_bfe_u32 v254, v203, 5, 1
	v_lshl_add_u32 v254, v254, 4, v183
	v_lshrrev_b32_e32 v254, 1, v254
	global_load_dwordx4 v[64:67], v186, s[26:27]
	global_load_dwordx4 v[68:71], v254, s[24:25]
	global_load_dwordx4 v[72:75], v186, s[26:27] offset:32
	global_load_dwordx4 v[76:79], v254, s[24:25] offset:32
	global_load_dwordx4 v[80:83], v186, s[26:27] offset:64
	global_load_dwordx4 v[84:87], v254, s[24:25] offset:64
	global_load_dwordx4 v[88:91], v186, s[26:27] offset:96
	global_load_dwordx4 v[92:95], v254, s[24:25] offset:96
	global_load_dwordx4 v[96:99], v186, s[26:27] offset:128
	global_load_dwordx4 v[100:103], v254, s[24:25] offset:128
	global_load_dwordx4 v[104:107], v186, s[26:27] offset:160
	global_load_dwordx4 v[204:207], v254, s[24:25] offset:160
	global_load_dwordx4 v[208:211], v186, s[26:27] offset:192
	global_load_dwordx4 v[212:215], v254, s[24:25] offset:192
	global_load_dwordx4 v[216:219], v186, s[26:27] offset:224
	global_load_dwordx4 v[220:223], v254, s[24:25] offset:224
	s_waitcnt vmcnt(36)
	v_mfma_f32_32x32x16_bf16 v[224:239], v[0:3], v[4:7], v[224:239]
	v_mfma_f32_32x32x16_bf16 v[224:239], v[8:11], v[12:15], v[224:239]
	v_mfma_f32_32x32x16_bf16 v[224:239], v[16:19], v[20:23], v[224:239]
	v_mfma_f32_32x32x16_bf16 v[224:239], v[24:27], v[28:31], v[224:239]
	v_mfma_f32_32x32x16_bf16 v[224:239], v[32:35], v[36:39], v[224:239]
	v_mfma_f32_32x32x16_bf16 v[224:239], v[40:43], v[44:47], v[224:239]
	v_mfma_f32_32x32x16_bf16 v[224:239], v[48:51], v[52:55], v[224:239]
	v_mfma_f32_32x32x16_bf16 v[224:239], v[56:59], v[60:63], v[224:239]
	v_bfe_u32 v186, v203, 5, 1
	v_lshl_add_u32 v186, v186, 4, v182
	v_lshrrev_b32_e32 v186, 1, v186
	v_bfe_u32 v254, v203, 5, 1
	v_lshl_add_u32 v254, v254, 4, v183
	v_lshrrev_b32_e32 v254, 1, v254
	global_load_dwordx4 v[0:3], v186, s[26:27] offset:256
	global_load_dwordx4 v[4:7], v254, s[24:25] offset:256
	global_load_dwordx4 v[8:11], v186, s[26:27] offset:288
	global_load_dwordx4 v[12:15], v254, s[24:25] offset:288
	global_load_dwordx4 v[16:19], v186, s[26:27] offset:320
	global_load_dwordx4 v[20:23], v254, s[24:25] offset:320
	global_load_dwordx4 v[24:27], v186, s[26:27] offset:352
	global_load_dwordx4 v[28:31], v254, s[24:25] offset:352
	global_load_dwordx4 v[32:35], v186, s[26:27] offset:384
	global_load_dwordx4 v[36:39], v254, s[24:25] offset:384
	global_load_dwordx4 v[40:43], v186, s[26:27] offset:416
	global_load_dwordx4 v[44:47], v254, s[24:25] offset:416
	global_load_dwordx4 v[48:51], v186, s[26:27] offset:448
	global_load_dwordx4 v[52:55], v254, s[24:25] offset:448
	global_load_dwordx4 v[56:59], v186, s[26:27] offset:480
	global_load_dwordx4 v[60:63], v254, s[24:25] offset:480
	s_waitcnt vmcnt(36)
; DI unsigned pk2(float a, float b) { f32x2 v = {a, b}; bf2v r = __builtin_convertvector(v, bf2v); return __builtin_bit_cast(unsigned, r); }
; DI float bflo(unsigned w) { return __uint_as_float(w << 16); }
; DI float bfhi(unsigned w) { return __uint_as_float(w & 0xffff0000u); }
; #define MFMA32(a, b, c) __builtin_amdgcn_mfma_f32_32x32x16_bf16((a), (b), (c), 0, 0, 0)
; DI void sample_up_item(const Params& p, int item, int lane) {
;     ...
;         for (int c0 = 0; c0 < ld / 16; c0 += 16) {
;             bf16x8 wa[16], ga[16];
; #pragma unroll
;             for (int j = 0; j < 16; ++j) { wa[j] = *(const bf16x8*)(wp + 16 * (c0 + j)); ga[j] = *(const bf16x8*)(gp + 16 * (c0 + j)); }
;             __builtin_amdgcn_sched_barrier(0);
; #pragma unroll
;             for (int j = 0; j < 16; ++j) acc = MFMA32(wa[j], ga[j], acc);
;             __builtin_amdgcn_sched_barrier(0);
;         }
;         const bf16_t* sg = (const bf16_t*)(ws + OFF_SGS) + (size_t)(tok - T_P) * 3072 + br * 1024 + 32 * nb + 4 * hh;
; #pragma unroll
;         for (int g = 0; g < 4; ++g) {
;             const u32x2 z = *(const u32x2*)(sg + 8 * g);
;             tot[4 * g] += acc[4 * g] * bflo(z.x); tot[4 * g + 1] += acc[4 * g + 1] * bfhi(z.x); tot[4 * g + 2] += acc[4 * g + 2] * bflo(z.y); tot[4 * g + 3] += acc[4 * g + 3] * bfhi(z.y);
;         }
;     }
;     bf16_t* up = (bf16_t*)(ws + OFF_UB) + (size_t)tok * 1024 + 32 * nb + 4 * hh;
; #pragma unroll
;     for (int g = 0; g < 4; ++g) { u32x2 w; w.x = pk2(tot[4 * g], tot[4 * g + 1]); w.y = pk2(tot[4 * g + 2], tot[4 * g + 3]); *(u32x2*)(up + 8 * g) = w; }
; DI void p3_scan(const Params& p) {
;     ...
;     { int s0 = gw - 1024; if (s0 < 0) s0 += NGW; for (int it = s0; it < 512; it += NGW) sample_up_item(p, it, lane); }
	v_mfma_f32_32x32x16_bf16 v[224:239], v[116:119], v[120:123], v[224:239]
	v_mfma_f32_32x32x16_bf16 v[224:239], v[124:127], v[128:131], v[224:239]
	v_mfma_f32_32x32x16_bf16 v[224:239], v[132:135], v[136:139], v[224:239]
	v_mfma_f32_32x32x16_bf16 v[224:239], v[140:143], v[144:147], v[224:239]
	v_mfma_f32_32x32x16_bf16 v[224:239], v[148:151], v[152:155], v[224:239]
	v_mfma_f32_32x32x16_bf16 v[224:239], v[156:159], v[160:163], v[224:239]
	v_mfma_f32_32x32x16_bf16 v[224:239], v[164:167], v[168:171], v[224:239]
	v_mfma_f32_32x32x16_bf16 v[224:239], v[172:175], v[176:179], v[224:239]
	s_nop 7
	s_nop 3
	v_lshlrev_b32_e32 v186, 16, v248
	v_fma_f32 v190, v224, v186, v190
	v_and_b32_e32 v186, 0xffff0000, v248
	v_fma_f32 v191, v225, v186, v191
	v_lshlrev_b32_e32 v186, 16, v249
	v_fma_f32 v192, v226, v186, v192
	v_and_b32_e32 v186, 0xffff0000, v249
	v_fma_f32 v193, v227, v186, v193
	v_lshlrev_b32_e32 v186, 16, v250
	v_fma_f32 v194, v228, v186, v194
	v_and_b32_e32 v186, 0xffff0000, v250
	v_fma_f32 v195, v229, v186, v195
	v_lshlrev_b32_e32 v186, 16, v251
	v_fma_f32 v196, v230, v186, v196
	v_and_b32_e32 v186, 0xffff0000, v251
	v_fma_f32 v197, v231, v186, v197
	v_lshlrev_b32_e32 v186, 16, v252
	v_fma_f32 v198, v232, v186, v198
	v_and_b32_e32 v186, 0xffff0000, v252
	v_fma_f32 v199, v233, v186, v199
	v_lshlrev_b32_e32 v186, 16, v253
	v_fma_f32 v200, v234, v186, v200
	v_and_b32_e32 v186, 0xffff0000, v253
	v_fma_f32 v201, v235, v186, v201
	v_lshlrev_b32_e32 v186, 16, v180
	v_fma_f32 v202, v236, v186, v202
	v_and_b32_e32 v186, 0xffff0000, v180
	v_fma_f32 v108, v237, v186, v108
	v_lshlrev_b32_e32 v186, 16, v181
	v_fma_f32 v109, v238, v186, v109
	v_and_b32_e32 v186, 0xffff0000, v181
	v_fma_f32 v110, v239, v186, v110
	s_waitcnt vmcnt(16)
	v_mfma_f32_32x32x16_bf16 v[224:239], v[64:67], v[68:71], 0
	v_mfma_f32_32x32x16_bf16 v[224:239], v[72:75], v[76:79], v[224:239]
	v_mfma_f32_32x32x16_bf16 v[224:239], v[80:83], v[84:87], v[224:239]
	v_mfma_f32_32x32x16_bf16 v[224:239], v[88:91], v[92:95], v[224:239]
	v_mfma_f32_32x32x16_bf16 v[224:239], v[96:99], v[100:103], v[224:239]
	v_mfma_f32_32x32x16_bf16 v[224:239], v[104:107], v[204:207], v[224:239]
	v_mfma_f32_32x32x16_bf16 v[224:239], v[208:211], v[212:215], v[224:239]
	v_mfma_f32_32x32x16_bf16 v[224:239], v[216:219], v[220:223], v[224:239]
	s_waitcnt vmcnt(0)
	v_mfma_f32_32x32x16_bf16 v[224:239], v[0:3], v[4:7], v[224:239]
	v_mfma_f32_32x32x16_bf16 v[224:239], v[8:11], v[12:15], v[224:239]
	v_mfma_f32_32x32x16_bf16 v[224:239], v[16:19], v[20:23], v[224:239]
	v_mfma_f32_32x32x16_bf16 v[224:239], v[24:27], v[28:31], v[224:239]
	v_mfma_f32_32x32x16_bf16 v[224:239], v[32:35], v[36:39], v[224:239]
	v_mfma_f32_32x32x16_bf16 v[224:239], v[40:43], v[44:47], v[224:239]
	v_mfma_f32_32x32x16_bf16 v[224:239], v[48:51], v[52:55], v[224:239]
	v_mfma_f32_32x32x16_bf16 v[224:239], v[56:59], v[60:63], v[224:239]
	s_nop 7
	s_nop 3
	v_lshlrev_b32_e32 v186, 16, v240
	v_fma_f32 v190, v224, v186, v190
	v_and_b32_e32 v186, 0xffff0000, v240
	v_fma_f32 v191, v225, v186, v191
	v_lshlrev_b32_e32 v186, 16, v241
	v_fma_f32 v192, v226, v186, v192
	v_and_b32_e32 v186, 0xffff0000, v241
	v_fma_f32 v193, v227, v186, v193
	v_lshlrev_b32_e32 v186, 16, v242
	v_fma_f32 v194, v228, v186, v194
	v_and_b32_e32 v186, 0xffff0000, v242
	v_fma_f32 v195, v229, v186, v195
	v_lshlrev_b32_e32 v186, 16, v243
	v_fma_f32 v196, v230, v186, v196
	v_and_b32_e32 v186, 0xffff0000, v243
	v_fma_f32 v197, v231, v186, v197
	v_lshlrev_b32_e32 v186, 16, v244
	v_fma_f32 v198, v232, v186, v198
	v_and_b32_e32 v186, 0xffff0000, v244
	v_fma_f32 v199, v233, v186, v199
	v_lshlrev_b32_e32 v186, 16, v245
	v_fma_f32 v200, v234, v186, v200
	v_and_b32_e32 v186, 0xffff0000, v245
	v_fma_f32 v201, v235, v186, v201
	v_lshlrev_b32_e32 v186, 16, v246
	v_fma_f32 v202, v236, v186, v202
	v_and_b32_e32 v186, 0xffff0000, v246
	v_fma_f32 v108, v237, v186, v108
	v_lshlrev_b32_e32 v186, 16, v247
	v_fma_f32 v109, v238, v186, v109
	v_and_b32_e32 v186, 0xffff0000, v247
	v_fma_f32 v110, v239, v186, v110
	v_cvt_pk_bf16_f32 v224, v190, v191
	v_cvt_pk_bf16_f32 v225, v192, v193
	global_store_dwordx2 v185, v[224:225], s[30:31]
	v_cvt_pk_bf16_f32 v226, v194, v195
	v_cvt_pk_bf16_f32 v227, v196, v197
	global_store_dwordx2 v185, v[226:227], s[30:31] offset:16
	v_cvt_pk_bf16_f32 v228, v198, v199
	v_cvt_pk_bf16_f32 v229, v200, v201
	global_store_dwordx2 v185, v[228:229], s[30:31] offset:32
	v_cvt_pk_bf16_f32 v230, v202, v108
	v_cvt_pk_bf16_f32 v231, v109, v110
	global_store_dwordx2 v185, v[230:231], s[30:31] offset:48
	s_add_i32 s12, s12, s74
	s_cmpk_gt_i32 s12, 0x1ff
	s_cbranch_scc0 .Lsup_item
